# out-proj and FFN-down K-loops shifted by 4 bytes (s_nop before and after the loop) so their MFMA blocks sit like the other phases
# baseline (speedup 1.0000x reference)
.LBB0_1854:
	s_ashr_i32 s19, s18, 31
	s_lshl_b64 s[20:21], s[18:19], 21
	s_add_u32 s20, s33, s20
	s_addc_u32 s21, s34, s21
	s_and_b64 s[22:23], s[0:1], exec
	s_cselect_b32 s19, s21, s25
	s_cselect_b32 s51, s20, s24
	s_ashr_i32 s17, s16, 31
	s_lshl_b64 s[22:23], s[16:17], 21
	s_add_u32 s22, s35, s22
	s_addc_u32 s23, s36, s23
	s_and_b64 s[28:29], s[0:1], exec
	s_cselect_b32 s17, s23, s27
	s_cselect_b32 s52, s22, s26
	s_add_u32 s53, s26, 0x100
	v_mov_b32_e32 v2, 0
	s_addc_u32 s54, s27, 0
	s_mov_b32 s55, -2
	s_waitcnt lgkmcnt(0)
	v_mov_b32_e32 v3, v2
	v_mov_b32_e32 v4, v2
	v_mov_b32_e32 v5, v2
	v_mov_b32_e32 v6, v2
	v_mov_b32_e32 v7, v2
	v_mov_b32_e32 v8, v2
	v_mov_b32_e32 v9, v2
	v_mov_b32_e32 v18, v2
	v_mov_b32_e32 v19, v2
	v_mov_b32_e32 v20, v2
	v_mov_b32_e32 v21, v2
	v_mov_b32_e32 v22, v2
	v_mov_b32_e32 v23, v2
	v_mov_b32_e32 v24, v2
	v_mov_b32_e32 v25, v2
	v_mov_b32_e32 v34, v2
	v_mov_b32_e32 v35, v2
	v_mov_b32_e32 v36, v2
	v_mov_b32_e32 v37, v2
	v_mov_b32_e32 v38, v2
	v_mov_b32_e32 v39, v2
	v_mov_b32_e32 v40, v2
	v_mov_b32_e32 v41, v2
	v_mov_b32_e32 v50, v2
	v_mov_b32_e32 v51, v2
	v_mov_b32_e32 v52, v2
	v_mov_b32_e32 v53, v2
	v_mov_b32_e32 v54, v2
	v_mov_b32_e32 v55, v2
	v_mov_b32_e32 v56, v2
	v_mov_b32_e32 v57, v2
	v_mov_b32_e32 v10, v2
	v_mov_b32_e32 v11, v2
	v_mov_b32_e32 v12, v2
	v_mov_b32_e32 v13, v2
	v_mov_b32_e32 v14, v2
	v_mov_b32_e32 v15, v2
	v_mov_b32_e32 v16, v2
	v_mov_b32_e32 v17, v2
	v_mov_b32_e32 v26, v2
	v_mov_b32_e32 v27, v2
	v_mov_b32_e32 v28, v2
	v_mov_b32_e32 v29, v2
	v_mov_b32_e32 v30, v2
	v_mov_b32_e32 v31, v2
	v_mov_b32_e32 v32, v2
	v_mov_b32_e32 v33, v2
	v_mov_b32_e32 v42, v2
	v_mov_b32_e32 v43, v2
	v_mov_b32_e32 v44, v2
	v_mov_b32_e32 v45, v2
	v_mov_b32_e32 v46, v2
	v_mov_b32_e32 v47, v2
	v_mov_b32_e32 v48, v2
	v_mov_b32_e32 v49, v2
	v_mov_b32_e32 v58, v2
	v_mov_b32_e32 v59, v2
	v_mov_b32_e32 v60, v2
	v_mov_b32_e32 v61, v2
	v_mov_b32_e32 v62, v2
	v_mov_b32_e32 v63, v2
	v_mov_b32_e32 v64, v2
	v_mov_b32_e32 v65, v2
	v_mov_b32_e32 v66, v2
	v_mov_b32_e32 v67, v2
	v_mov_b32_e32 v68, v2
	v_mov_b32_e32 v69, v2
	v_mov_b32_e32 v70, v2
	v_mov_b32_e32 v71, v2
	v_mov_b32_e32 v72, v2
	v_mov_b32_e32 v73, v2
	v_mov_b32_e32 v82, v2
	v_mov_b32_e32 v83, v2
	v_mov_b32_e32 v84, v2
	v_mov_b32_e32 v85, v2
	v_mov_b32_e32 v86, v2
	v_mov_b32_e32 v87, v2
	v_mov_b32_e32 v88, v2
	v_mov_b32_e32 v89, v2
	v_mov_b32_e32 v98, v2
	v_mov_b32_e32 v99, v2
	v_mov_b32_e32 v100, v2
	v_mov_b32_e32 v101, v2
	v_mov_b32_e32 v102, v2
	v_mov_b32_e32 v103, v2
	v_mov_b32_e32 v104, v2
	v_mov_b32_e32 v105, v2
	v_mov_b32_e32 v114, v2
	v_mov_b32_e32 v115, v2
	v_mov_b32_e32 v116, v2
	v_mov_b32_e32 v117, v2
	v_mov_b32_e32 v118, v2
	v_mov_b32_e32 v119, v2
	v_mov_b32_e32 v120, v2
	v_mov_b32_e32 v121, v2
	v_mov_b32_e32 v74, v2
	v_mov_b32_e32 v75, v2
	v_mov_b32_e32 v76, v2
	v_mov_b32_e32 v77, v2
	v_mov_b32_e32 v78, v2
	v_mov_b32_e32 v79, v2
	v_mov_b32_e32 v80, v2
	v_mov_b32_e32 v81, v2
	v_mov_b32_e32 v90, v2
	v_mov_b32_e32 v91, v2
	v_mov_b32_e32 v92, v2
	v_mov_b32_e32 v93, v2
	v_mov_b32_e32 v94, v2
	v_mov_b32_e32 v95, v2
	v_mov_b32_e32 v96, v2
	v_mov_b32_e32 v97, v2
	v_mov_b32_e32 v106, v2
	v_mov_b32_e32 v107, v2
	v_mov_b32_e32 v108, v2
	v_mov_b32_e32 v109, v2
	v_mov_b32_e32 v110, v2
	v_mov_b32_e32 v111, v2
	v_mov_b32_e32 v112, v2
	v_mov_b32_e32 v113, v2
	v_mov_b32_e32 v122, v2
	v_mov_b32_e32 v123, v2
	v_mov_b32_e32 v124, v2
	v_mov_b32_e32 v125, v2
	v_mov_b32_e32 v126, v2
	v_mov_b32_e32 v127, v2
	v_mov_b32_e32 v128, v2
	v_mov_b32_e32 v129, v2
	s_nop 0
.LBB0_1855:
	ds_read_b128 v[142:145], v148
	ds_read_b128 v[152:155], v148 offset:1024
	ds_read_b128 v[156:159], v148 offset:2048
	ds_read_b128 v[160:163], v148 offset:3072
	ds_read_b128 v[164:167], v149
	ds_read_b128 v[168:171], v149 offset:1024
	ds_read_b128 v[172:175], v149 offset:2048
	ds_read_b128 v[176:179], v149 offset:3072
	s_add_u32 s26, s24, 0x100
	s_addc_u32 s27, s25, 0
	s_cmp_eq_u32 s55, 60
	s_cselect_b32 s31, s19, s27
	s_cselect_b32 s30, s51, s26
	s_cselect_b32 s29, s17, s54
	s_cselect_b32 s28, s52, s53
	v_lshl_add_u64 v[212:213], s[24:25], 0, v[134:135]
	s_add_i32 m0, s5, 0xc000
	ds_read_b128 v[180:183], v150
	ds_read_b128 v[184:187], v150 offset:1024
	ds_read_b128 v[188:191], v150 offset:2048
	ds_read_b128 v[192:195], v150 offset:3072
	ds_read_b128 v[196:199], v150 offset:4096
	ds_read_b128 v[200:203], v150 offset:5120
	ds_read_b128 v[204:207], v150 offset:6144
	ds_read_b128 v[208:211], v150 offset:7168
	global_load_lds_dwordx4 v[212:213], off
	v_lshl_add_u64 v[212:213], s[24:25], 0, v[136:137]
	s_add_i32 m0, s5, 0xe000
	s_nop 0
	global_load_lds_dwordx4 v[212:213], off
	s_waitcnt vmcnt(8)
	s_waitcnt lgkmcnt(0)
	s_barrier
	s_setprio 1
	s_waitcnt lgkmcnt(0)
	v_mfma_f32_16x16x32_bf16 v[126:129], v[142:145], v[180:183], v[126:129]
	v_mfma_f32_16x16x32_bf16 v[122:125], v[156:159], v[180:183], v[122:125]
	v_mfma_f32_16x16x32_bf16 v[110:113], v[142:145], v[188:191], v[110:113]
	v_mfma_f32_16x16x32_bf16 v[106:109], v[156:159], v[188:191], v[106:109]
	v_mfma_f32_16x16x32_bf16 v[94:97], v[142:145], v[196:199], v[94:97]
	v_mfma_f32_16x16x32_bf16 v[90:93], v[156:159], v[196:199], v[90:93]
	v_mfma_f32_16x16x32_bf16 v[78:81], v[142:145], v[204:207], v[78:81]
	v_mfma_f32_16x16x32_bf16 v[74:77], v[156:159], v[204:207], v[74:77]
	v_mfma_f32_16x16x32_bf16 v[126:129], v[152:155], v[184:187], v[126:129]
	v_mfma_f32_16x16x32_bf16 v[122:125], v[160:163], v[184:187], v[122:125]
	v_mfma_f32_16x16x32_bf16 v[110:113], v[152:155], v[192:195], v[110:113]
	v_mfma_f32_16x16x32_bf16 v[106:109], v[160:163], v[192:195], v[106:109]
	v_mfma_f32_16x16x32_bf16 v[94:97], v[152:155], v[200:203], v[94:97]
	v_mfma_f32_16x16x32_bf16 v[90:93], v[160:163], v[200:203], v[90:93]
	v_mfma_f32_16x16x32_bf16 v[78:81], v[152:155], v[208:211], v[78:81]
	v_mfma_f32_16x16x32_bf16 v[74:77], v[160:163], v[208:211], v[74:77]
	s_setprio 0
	s_setprio 1
	v_mfma_f32_16x16x32_bf16 v[118:121], v[164:167], v[180:183], v[118:121]
	v_mfma_f32_16x16x32_bf16 v[114:117], v[172:175], v[180:183], v[114:117]
	v_mfma_f32_16x16x32_bf16 v[102:105], v[164:167], v[188:191], v[102:105]
	v_mfma_f32_16x16x32_bf16 v[98:101], v[172:175], v[188:191], v[98:101]
	v_mfma_f32_16x16x32_bf16 v[86:89], v[164:167], v[196:199], v[86:89]
	v_mfma_f32_16x16x32_bf16 v[82:85], v[172:175], v[196:199], v[82:85]
	v_mfma_f32_16x16x32_bf16 v[70:73], v[164:167], v[204:207], v[70:73]
	v_mfma_f32_16x16x32_bf16 v[66:69], v[172:175], v[204:207], v[66:69]
	v_mfma_f32_16x16x32_bf16 v[118:121], v[168:171], v[184:187], v[118:121]
	v_mfma_f32_16x16x32_bf16 v[114:117], v[176:179], v[184:187], v[114:117]
	v_mfma_f32_16x16x32_bf16 v[102:105], v[168:171], v[192:195], v[102:105]
	v_mfma_f32_16x16x32_bf16 v[98:101], v[176:179], v[192:195], v[98:101]
	v_mfma_f32_16x16x32_bf16 v[86:89], v[168:171], v[200:203], v[86:89]
	v_mfma_f32_16x16x32_bf16 v[82:85], v[176:179], v[200:203], v[82:85]
	v_mfma_f32_16x16x32_bf16 v[70:73], v[168:171], v[208:211], v[70:73]
	v_mfma_f32_16x16x32_bf16 v[66:69], v[176:179], v[208:211], v[66:69]
	s_setprio 0
	s_barrier
	s_add_i32 s24, s48, s37
	v_lshl_add_u64 v[212:213], s[28:29], 0, v[130:131]
	s_mov_b32 m0, s24
	ds_read_b128 v[180:183], v150 offset:16384
	ds_read_b128 v[184:187], v150 offset:17408
	ds_read_b128 v[188:191], v150 offset:18432
	ds_read_b128 v[192:195], v150 offset:19456
	ds_read_b128 v[196:199], v150 offset:20480
	ds_read_b128 v[200:203], v150 offset:21504
	ds_read_b128 v[204:207], v150 offset:22528
	ds_read_b128 v[208:211], v150 offset:23552
	global_load_lds_dwordx4 v[212:213], off
	s_add_i32 m0, s24, 0x2000
	s_add_u32 s24, s28, 0x100000
	v_lshl_add_u64 v[214:215], s[28:29], 0, v[132:133]
	s_addc_u32 s25, s29, 0
	s_add_i32 s56, s49, s37
	global_load_lds_dwordx4 v[214:215], off
	v_lshl_add_u64 v[216:217], s[24:25], 0, v[130:131]
	s_mov_b32 m0, s56
	v_lshl_add_u64 v[218:219], s[30:31], 0, v[132:133]
	global_load_lds_dwordx4 v[216:217], off
	v_lshl_add_u64 v[216:217], s[24:25], 0, v[132:133]
	s_add_i32 m0, s56, 0x2000
	s_nop 0
	global_load_lds_dwordx4 v[216:217], off
	v_lshl_add_u64 v[216:217], s[30:31], 0, v[130:131]
	s_mov_b32 m0, s5
	s_nop 0
	global_load_lds_dwordx4 v[216:217], off
	s_mov_b32 m0, s38
	s_nop 0
	global_load_lds_dwordx4 v[218:219], off
	s_waitcnt vmcnt(8)
	s_waitcnt lgkmcnt(0)
	s_barrier
	s_setprio 1
	s_waitcnt lgkmcnt(0)
	v_mfma_f32_16x16x32_bf16 v[62:65], v[142:145], v[180:183], v[62:65]
	v_mfma_f32_16x16x32_bf16 v[58:61], v[156:159], v[180:183], v[58:61]
	v_mfma_f32_16x16x32_bf16 v[46:49], v[142:145], v[188:191], v[46:49]
	v_mfma_f32_16x16x32_bf16 v[42:45], v[156:159], v[188:191], v[42:45]
	v_mfma_f32_16x16x32_bf16 v[30:33], v[142:145], v[196:199], v[30:33]
	v_mfma_f32_16x16x32_bf16 v[26:29], v[156:159], v[196:199], v[26:29]
	v_mfma_f32_16x16x32_bf16 v[14:17], v[142:145], v[204:207], v[14:17]
	v_mfma_f32_16x16x32_bf16 v[10:13], v[156:159], v[204:207], v[10:13]
	v_mfma_f32_16x16x32_bf16 v[62:65], v[152:155], v[184:187], v[62:65]
	v_mfma_f32_16x16x32_bf16 v[58:61], v[160:163], v[184:187], v[58:61]
	v_mfma_f32_16x16x32_bf16 v[46:49], v[152:155], v[192:195], v[46:49]
	v_mfma_f32_16x16x32_bf16 v[42:45], v[160:163], v[192:195], v[42:45]
	v_mfma_f32_16x16x32_bf16 v[30:33], v[152:155], v[200:203], v[30:33]
	v_mfma_f32_16x16x32_bf16 v[26:29], v[160:163], v[200:203], v[26:29]
	v_mfma_f32_16x16x32_bf16 v[14:17], v[152:155], v[208:211], v[14:17]
	v_mfma_f32_16x16x32_bf16 v[10:13], v[160:163], v[208:211], v[10:13]
	s_setprio 0
	s_setprio 1
	v_mfma_f32_16x16x32_bf16 v[54:57], v[164:167], v[180:183], v[54:57]
	v_mfma_f32_16x16x32_bf16 v[50:53], v[172:175], v[180:183], v[50:53]
	v_mfma_f32_16x16x32_bf16 v[38:41], v[164:167], v[188:191], v[38:41]
	v_mfma_f32_16x16x32_bf16 v[34:37], v[172:175], v[188:191], v[34:37]
	v_mfma_f32_16x16x32_bf16 v[22:25], v[164:167], v[196:199], v[22:25]
	v_mfma_f32_16x16x32_bf16 v[18:21], v[172:175], v[196:199], v[18:21]
	v_mfma_f32_16x16x32_bf16 v[6:9], v[164:167], v[204:207], v[6:9]
	v_mfma_f32_16x16x32_bf16 v[2:5], v[172:175], v[204:207], v[2:5]
	v_mfma_f32_16x16x32_bf16 v[54:57], v[168:171], v[184:187], v[54:57]
	v_mfma_f32_16x16x32_bf16 v[50:53], v[176:179], v[184:187], v[50:53]
	v_mfma_f32_16x16x32_bf16 v[38:41], v[168:171], v[192:195], v[38:41]
	v_mfma_f32_16x16x32_bf16 v[34:37], v[176:179], v[192:195], v[34:37]
	v_mfma_f32_16x16x32_bf16 v[22:25], v[168:171], v[200:203], v[22:25]
	v_mfma_f32_16x16x32_bf16 v[18:21], v[176:179], v[200:203], v[18:21]
	v_mfma_f32_16x16x32_bf16 v[6:9], v[168:171], v[208:211], v[6:9]
	v_mfma_f32_16x16x32_bf16 v[2:5], v[176:179], v[208:211], v[2:5]
	s_setprio 0
	s_barrier
	s_add_i32 s56, 0, 0x18000
	s_add_i32 s57, 0, 0x1c000
	v_add_u32_e32 v160, s56, v147
	v_add_u32_e32 v176, s57, v147
	ds_read_b128 v[142:145], v160
	ds_read_b128 v[152:155], v160 offset:1024
	ds_read_b128 v[156:159], v160 offset:2048
	ds_read_b128 v[160:163], v160 offset:3072
	ds_read_b128 v[164:167], v176
	ds_read_b128 v[168:171], v176 offset:1024
	ds_read_b128 v[172:175], v176 offset:2048
	ds_read_b128 v[176:179], v176 offset:3072
	s_add_u32 s24, s30, 0x100000
	s_addc_u32 s25, s31, 0
	s_mov_b32 m0, s39
	v_lshl_add_u64 v[220:221], s[24:25], 0, v[130:131]
	ds_read_b128 v[180:183], v150 offset:32768
	ds_read_b128 v[184:187], v150 offset:33792
	ds_read_b128 v[188:191], v150 offset:34816
	ds_read_b128 v[192:195], v150 offset:35840
	ds_read_b128 v[196:199], v150 offset:36864
	ds_read_b128 v[200:203], v150 offset:37888
	ds_read_b128 v[204:207], v150 offset:38912
	ds_read_b128 v[208:211], v150 offset:39936
	global_load_lds_dwordx4 v[220:221], off
	v_lshl_add_u64 v[220:221], s[24:25], 0, v[132:133]
	s_mov_b32 m0, s40
	s_nop 0
	global_load_lds_dwordx4 v[220:221], off
	s_waitcnt vmcnt(8)
	s_waitcnt lgkmcnt(0)
	s_barrier
	s_setprio 1
	s_waitcnt lgkmcnt(0)
	v_mfma_f32_16x16x32_bf16 v[126:129], v[142:145], v[180:183], v[126:129]
	v_mfma_f32_16x16x32_bf16 v[122:125], v[156:159], v[180:183], v[122:125]
	v_mfma_f32_16x16x32_bf16 v[110:113], v[142:145], v[188:191], v[110:113]
	v_mfma_f32_16x16x32_bf16 v[106:109], v[156:159], v[188:191], v[106:109]
	v_mfma_f32_16x16x32_bf16 v[94:97], v[142:145], v[196:199], v[94:97]
	v_mfma_f32_16x16x32_bf16 v[90:93], v[156:159], v[196:199], v[90:93]
	v_mfma_f32_16x16x32_bf16 v[78:81], v[142:145], v[204:207], v[78:81]
	v_mfma_f32_16x16x32_bf16 v[74:77], v[156:159], v[204:207], v[74:77]
	v_mfma_f32_16x16x32_bf16 v[126:129], v[152:155], v[184:187], v[126:129]
	v_mfma_f32_16x16x32_bf16 v[122:125], v[160:163], v[184:187], v[122:125]
	v_mfma_f32_16x16x32_bf16 v[110:113], v[152:155], v[192:195], v[110:113]
	v_mfma_f32_16x16x32_bf16 v[106:109], v[160:163], v[192:195], v[106:109]
	v_mfma_f32_16x16x32_bf16 v[94:97], v[152:155], v[200:203], v[94:97]
	v_mfma_f32_16x16x32_bf16 v[90:93], v[160:163], v[200:203], v[90:93]
	v_mfma_f32_16x16x32_bf16 v[78:81], v[152:155], v[208:211], v[78:81]
	v_mfma_f32_16x16x32_bf16 v[74:77], v[160:163], v[208:211], v[74:77]
	s_setprio 0
	s_setprio 1
	v_mfma_f32_16x16x32_bf16 v[118:121], v[164:167], v[180:183], v[118:121]
	v_mfma_f32_16x16x32_bf16 v[114:117], v[172:175], v[180:183], v[114:117]
	v_mfma_f32_16x16x32_bf16 v[102:105], v[164:167], v[188:191], v[102:105]
	v_mfma_f32_16x16x32_bf16 v[98:101], v[172:175], v[188:191], v[98:101]
	v_mfma_f32_16x16x32_bf16 v[86:89], v[164:167], v[196:199], v[86:89]
	v_mfma_f32_16x16x32_bf16 v[82:85], v[172:175], v[196:199], v[82:85]
	v_mfma_f32_16x16x32_bf16 v[70:73], v[164:167], v[204:207], v[70:73]
	v_mfma_f32_16x16x32_bf16 v[66:69], v[172:175], v[204:207], v[66:69]
	v_mfma_f32_16x16x32_bf16 v[118:121], v[168:171], v[184:187], v[118:121]
	v_mfma_f32_16x16x32_bf16 v[114:117], v[176:179], v[184:187], v[114:117]
	v_mfma_f32_16x16x32_bf16 v[102:105], v[168:171], v[192:195], v[102:105]
	v_mfma_f32_16x16x32_bf16 v[98:101], v[176:179], v[192:195], v[98:101]
	v_mfma_f32_16x16x32_bf16 v[86:89], v[168:171], v[200:203], v[86:89]
	v_mfma_f32_16x16x32_bf16 v[82:85], v[176:179], v[200:203], v[82:85]
	v_mfma_f32_16x16x32_bf16 v[70:73], v[168:171], v[208:211], v[70:73]
	v_mfma_f32_16x16x32_bf16 v[66:69], v[176:179], v[208:211], v[66:69]
	s_setprio 0
	s_barrier
	s_add_i32 s24, s56, s37
	v_lshl_add_u64 v[212:213], v[212:213], 0, s[12:13]
	s_mov_b32 m0, s24
	ds_read_b128 v[180:183], v150 offset:49152
	ds_read_b128 v[184:187], v150 offset:50176
	ds_read_b128 v[188:191], v150 offset:51200
	ds_read_b128 v[192:195], v150 offset:52224
	ds_read_b128 v[196:199], v150 offset:53248
	ds_read_b128 v[200:203], v150 offset:54272
	ds_read_b128 v[204:207], v150 offset:55296
	ds_read_b128 v[208:211], v150 offset:56320
	global_load_lds_dwordx4 v[212:213], off
	s_add_i32 m0, s24, 0x2000
	s_add_u32 s24, s28, 0x100080
	v_lshl_add_u64 v[212:213], v[214:215], 0, s[12:13]
	s_addc_u32 s25, s29, 0
	s_add_i32 s28, s57, s37
	global_load_lds_dwordx4 v[212:213], off
	v_lshl_add_u64 v[212:213], s[24:25], 0, v[130:131]
	s_mov_b32 m0, s28
	s_nop 0
	global_load_lds_dwordx4 v[212:213], off
	v_lshl_add_u64 v[212:213], s[24:25], 0, v[132:133]
	s_add_i32 m0, s28, 0x2000
	s_nop 0
	global_load_lds_dwordx4 v[212:213], off
	v_lshl_add_u64 v[212:213], v[216:217], 0, s[12:13]
	s_mov_b32 m0, s44
	s_nop 0
	global_load_lds_dwordx4 v[212:213], off
	v_lshl_add_u64 v[212:213], v[218:219], 0, s[12:13]
	s_mov_b32 m0, s45
	s_nop 0
	global_load_lds_dwordx4 v[212:213], off
	s_waitcnt vmcnt(8)
	s_waitcnt lgkmcnt(0)
	s_barrier
	s_setprio 1
	s_waitcnt lgkmcnt(0)
	v_mfma_f32_16x16x32_bf16 v[62:65], v[142:145], v[180:183], v[62:65]
	v_mfma_f32_16x16x32_bf16 v[58:61], v[156:159], v[180:183], v[58:61]
	v_mfma_f32_16x16x32_bf16 v[46:49], v[142:145], v[188:191], v[46:49]
	v_mfma_f32_16x16x32_bf16 v[42:45], v[156:159], v[188:191], v[42:45]
	v_mfma_f32_16x16x32_bf16 v[30:33], v[142:145], v[196:199], v[30:33]
	v_mfma_f32_16x16x32_bf16 v[26:29], v[156:159], v[196:199], v[26:29]
	v_mfma_f32_16x16x32_bf16 v[14:17], v[142:145], v[204:207], v[14:17]
	v_mfma_f32_16x16x32_bf16 v[10:13], v[156:159], v[204:207], v[10:13]
	v_mfma_f32_16x16x32_bf16 v[62:65], v[152:155], v[184:187], v[62:65]
	v_mfma_f32_16x16x32_bf16 v[58:61], v[160:163], v[184:187], v[58:61]
	v_mfma_f32_16x16x32_bf16 v[46:49], v[152:155], v[192:195], v[46:49]
	v_mfma_f32_16x16x32_bf16 v[42:45], v[160:163], v[192:195], v[42:45]
	v_mfma_f32_16x16x32_bf16 v[30:33], v[152:155], v[200:203], v[30:33]
	v_mfma_f32_16x16x32_bf16 v[26:29], v[160:163], v[200:203], v[26:29]
	v_mfma_f32_16x16x32_bf16 v[14:17], v[152:155], v[208:211], v[14:17]
	v_mfma_f32_16x16x32_bf16 v[10:13], v[160:163], v[208:211], v[10:13]
	s_setprio 0
	s_setprio 1
	v_mfma_f32_16x16x32_bf16 v[54:57], v[164:167], v[180:183], v[54:57]
	v_mfma_f32_16x16x32_bf16 v[50:53], v[172:175], v[180:183], v[50:53]
	v_mfma_f32_16x16x32_bf16 v[38:41], v[164:167], v[188:191], v[38:41]
	v_mfma_f32_16x16x32_bf16 v[34:37], v[172:175], v[188:191], v[34:37]
	v_mfma_f32_16x16x32_bf16 v[22:25], v[164:167], v[196:199], v[22:25]
	v_mfma_f32_16x16x32_bf16 v[18:21], v[172:175], v[196:199], v[18:21]
	v_mfma_f32_16x16x32_bf16 v[6:9], v[164:167], v[204:207], v[6:9]
	v_mfma_f32_16x16x32_bf16 v[2:5], v[172:175], v[204:207], v[2:5]
	v_mfma_f32_16x16x32_bf16 v[54:57], v[168:171], v[184:187], v[54:57]
	v_mfma_f32_16x16x32_bf16 v[50:53], v[176:179], v[184:187], v[50:53]
	v_mfma_f32_16x16x32_bf16 v[38:41], v[168:171], v[192:195], v[38:41]
	v_mfma_f32_16x16x32_bf16 v[34:37], v[176:179], v[192:195], v[34:37]
	v_mfma_f32_16x16x32_bf16 v[22:25], v[168:171], v[200:203], v[22:25]
	v_mfma_f32_16x16x32_bf16 v[18:21], v[176:179], v[200:203], v[18:21]
	v_mfma_f32_16x16x32_bf16 v[6:9], v[168:171], v[208:211], v[6:9]
	v_mfma_f32_16x16x32_bf16 v[2:5], v[176:179], v[208:211], v[2:5]
	s_setprio 0
	s_barrier
	s_add_i32 s55, s55, 2
	s_add_u32 s53, s53, 0x100
	s_addc_u32 s54, s54, 0
	s_cmp_gt_u32 s55, 61
	s_mov_b64 s[24:25], s[26:27]
	s_cbranch_scc0 .LBB0_1855
	s_nop 0
	s_and_b64 vcc, exec, s[14:15]
	s_cbranch_vccz .LBB0_1858
	s_barrier

.LBB0_2117:
	s_add_u32 s47, s20, 0x100
	v_mov_b32_e32 v2, 0
	s_addc_u32 s48, s21, 0
	s_mov_b32 s49, -2
	s_waitcnt lgkmcnt(0)
	v_mov_b32_e32 v3, v2
	v_mov_b32_e32 v4, v2
	v_mov_b32_e32 v5, v2
	v_mov_b32_e32 v6, v2
	v_mov_b32_e32 v7, v2
	v_mov_b32_e32 v8, v2
	v_mov_b32_e32 v9, v2
	v_mov_b32_e32 v18, v2
	v_mov_b32_e32 v19, v2
	v_mov_b32_e32 v20, v2
	v_mov_b32_e32 v21, v2
	v_mov_b32_e32 v22, v2
	v_mov_b32_e32 v23, v2
	v_mov_b32_e32 v24, v2
	v_mov_b32_e32 v25, v2
	v_mov_b32_e32 v34, v2
	v_mov_b32_e32 v35, v2
	v_mov_b32_e32 v36, v2
	v_mov_b32_e32 v37, v2
	v_mov_b32_e32 v38, v2
	v_mov_b32_e32 v39, v2
	v_mov_b32_e32 v40, v2
	v_mov_b32_e32 v41, v2
	v_mov_b32_e32 v50, v2
	v_mov_b32_e32 v51, v2
	v_mov_b32_e32 v52, v2
	v_mov_b32_e32 v53, v2
	v_mov_b32_e32 v54, v2
	v_mov_b32_e32 v55, v2
	v_mov_b32_e32 v56, v2
	v_mov_b32_e32 v57, v2
	v_mov_b32_e32 v10, v2
	v_mov_b32_e32 v11, v2
	v_mov_b32_e32 v12, v2
	v_mov_b32_e32 v13, v2
	v_mov_b32_e32 v14, v2
	v_mov_b32_e32 v15, v2
	v_mov_b32_e32 v16, v2
	v_mov_b32_e32 v17, v2
	v_mov_b32_e32 v26, v2
	v_mov_b32_e32 v27, v2
	v_mov_b32_e32 v28, v2
	v_mov_b32_e32 v29, v2
	v_mov_b32_e32 v30, v2
	v_mov_b32_e32 v31, v2
	v_mov_b32_e32 v32, v2
	v_mov_b32_e32 v33, v2
	v_mov_b32_e32 v42, v2
	v_mov_b32_e32 v43, v2
	v_mov_b32_e32 v44, v2
	v_mov_b32_e32 v45, v2
	v_mov_b32_e32 v46, v2
	v_mov_b32_e32 v47, v2
	v_mov_b32_e32 v48, v2
	v_mov_b32_e32 v49, v2
	v_mov_b32_e32 v58, v2
	v_mov_b32_e32 v59, v2
	v_mov_b32_e32 v60, v2
	v_mov_b32_e32 v61, v2
	v_mov_b32_e32 v62, v2
	v_mov_b32_e32 v63, v2
	v_mov_b32_e32 v64, v2
	v_mov_b32_e32 v65, v2
	v_mov_b32_e32 v66, v2
	v_mov_b32_e32 v67, v2
	v_mov_b32_e32 v68, v2
	v_mov_b32_e32 v69, v2
	v_mov_b32_e32 v70, v2
	v_mov_b32_e32 v71, v2
	v_mov_b32_e32 v72, v2
	v_mov_b32_e32 v73, v2
	v_mov_b32_e32 v82, v2
	v_mov_b32_e32 v83, v2
	v_mov_b32_e32 v84, v2
	v_mov_b32_e32 v85, v2
	v_mov_b32_e32 v86, v2
	v_mov_b32_e32 v87, v2
	v_mov_b32_e32 v88, v2
	v_mov_b32_e32 v89, v2
	v_mov_b32_e32 v98, v2
	v_mov_b32_e32 v99, v2
	v_mov_b32_e32 v100, v2
	v_mov_b32_e32 v101, v2
	v_mov_b32_e32 v102, v2
	v_mov_b32_e32 v103, v2
	v_mov_b32_e32 v104, v2
	v_mov_b32_e32 v105, v2
	v_mov_b32_e32 v114, v2
	v_mov_b32_e32 v115, v2
	v_mov_b32_e32 v116, v2
	v_mov_b32_e32 v117, v2
	v_mov_b32_e32 v118, v2
	v_mov_b32_e32 v119, v2
	v_mov_b32_e32 v120, v2
	v_mov_b32_e32 v121, v2
	v_mov_b32_e32 v74, v2
	v_mov_b32_e32 v75, v2
	v_mov_b32_e32 v76, v2
	v_mov_b32_e32 v77, v2
	v_mov_b32_e32 v78, v2
	v_mov_b32_e32 v79, v2
	v_mov_b32_e32 v80, v2
	v_mov_b32_e32 v81, v2
	v_mov_b32_e32 v90, v2
	v_mov_b32_e32 v91, v2
	v_mov_b32_e32 v92, v2
	v_mov_b32_e32 v93, v2
	v_mov_b32_e32 v94, v2
	v_mov_b32_e32 v95, v2
	v_mov_b32_e32 v96, v2
	v_mov_b32_e32 v97, v2
	v_mov_b32_e32 v106, v2
	v_mov_b32_e32 v107, v2
	v_mov_b32_e32 v108, v2
	v_mov_b32_e32 v109, v2
	v_mov_b32_e32 v110, v2
	v_mov_b32_e32 v111, v2
	v_mov_b32_e32 v112, v2
	v_mov_b32_e32 v113, v2
	v_mov_b32_e32 v122, v2
	v_mov_b32_e32 v123, v2
	v_mov_b32_e32 v124, v2
	v_mov_b32_e32 v125, v2
	v_mov_b32_e32 v126, v2
	v_mov_b32_e32 v127, v2
	v_mov_b32_e32 v128, v2
	v_mov_b32_e32 v129, v2
	s_nop 0
.LBB0_2118:
	ds_read_b128 v[142:145], v148
	ds_read_b128 v[152:155], v148 offset:1024
	ds_read_b128 v[156:159], v148 offset:2048
	ds_read_b128 v[160:163], v148 offset:3072
	ds_read_b128 v[164:167], v149
	ds_read_b128 v[168:171], v149 offset:1024
	ds_read_b128 v[172:175], v149 offset:2048
	ds_read_b128 v[176:179], v149 offset:3072
	s_add_u32 s20, s18, 0x100
	s_addc_u32 s21, s19, 0
	s_cmpk_eq_i32 s49, 0x54
	s_cselect_b32 s25, s7, s21
	s_cselect_b32 s24, s6, s20
	s_cselect_b32 s23, s17, s48
	s_cselect_b32 s22, s16, s47
	v_lshl_add_u64 v[212:213], s[18:19], 0, v[134:135]
	s_add_i32 m0, s30, 0xc000
	ds_read_b128 v[180:183], v150
	ds_read_b128 v[184:187], v150 offset:1024
	ds_read_b128 v[188:191], v150 offset:2048
	ds_read_b128 v[192:195], v150 offset:3072
	ds_read_b128 v[196:199], v150 offset:4096
	ds_read_b128 v[200:203], v150 offset:5120
	ds_read_b128 v[204:207], v150 offset:6144
	ds_read_b128 v[208:211], v150 offset:7168
	global_load_lds_dwordx4 v[212:213], off
	v_lshl_add_u64 v[212:213], s[18:19], 0, v[136:137]
	s_add_i32 m0, s30, 0xe000
	s_nop 0
	global_load_lds_dwordx4 v[212:213], off
	s_waitcnt vmcnt(8)
	s_waitcnt lgkmcnt(0)
	s_barrier
	s_setprio 1
	s_waitcnt lgkmcnt(0)
	v_mfma_f32_16x16x32_bf16 v[126:129], v[142:145], v[180:183], v[126:129]
	v_mfma_f32_16x16x32_bf16 v[122:125], v[156:159], v[180:183], v[122:125]
	v_mfma_f32_16x16x32_bf16 v[110:113], v[142:145], v[188:191], v[110:113]
	v_mfma_f32_16x16x32_bf16 v[106:109], v[156:159], v[188:191], v[106:109]
	v_mfma_f32_16x16x32_bf16 v[94:97], v[142:145], v[196:199], v[94:97]
	v_mfma_f32_16x16x32_bf16 v[90:93], v[156:159], v[196:199], v[90:93]
	v_mfma_f32_16x16x32_bf16 v[78:81], v[142:145], v[204:207], v[78:81]
	v_mfma_f32_16x16x32_bf16 v[74:77], v[156:159], v[204:207], v[74:77]
	v_mfma_f32_16x16x32_bf16 v[126:129], v[152:155], v[184:187], v[126:129]
	v_mfma_f32_16x16x32_bf16 v[122:125], v[160:163], v[184:187], v[122:125]
	v_mfma_f32_16x16x32_bf16 v[110:113], v[152:155], v[192:195], v[110:113]
	v_mfma_f32_16x16x32_bf16 v[106:109], v[160:163], v[192:195], v[106:109]
	v_mfma_f32_16x16x32_bf16 v[94:97], v[152:155], v[200:203], v[94:97]
	v_mfma_f32_16x16x32_bf16 v[90:93], v[160:163], v[200:203], v[90:93]
	v_mfma_f32_16x16x32_bf16 v[78:81], v[152:155], v[208:211], v[78:81]
	v_mfma_f32_16x16x32_bf16 v[74:77], v[160:163], v[208:211], v[74:77]
	s_setprio 0
	s_setprio 1
	v_mfma_f32_16x16x32_bf16 v[118:121], v[164:167], v[180:183], v[118:121]
	v_mfma_f32_16x16x32_bf16 v[114:117], v[172:175], v[180:183], v[114:117]
	v_mfma_f32_16x16x32_bf16 v[102:105], v[164:167], v[188:191], v[102:105]
	v_mfma_f32_16x16x32_bf16 v[98:101], v[172:175], v[188:191], v[98:101]
	v_mfma_f32_16x16x32_bf16 v[86:89], v[164:167], v[196:199], v[86:89]
	v_mfma_f32_16x16x32_bf16 v[82:85], v[172:175], v[196:199], v[82:85]
	v_mfma_f32_16x16x32_bf16 v[70:73], v[164:167], v[204:207], v[70:73]
	v_mfma_f32_16x16x32_bf16 v[66:69], v[172:175], v[204:207], v[66:69]
	v_mfma_f32_16x16x32_bf16 v[118:121], v[168:171], v[184:187], v[118:121]
	v_mfma_f32_16x16x32_bf16 v[114:117], v[176:179], v[184:187], v[114:117]
	v_mfma_f32_16x16x32_bf16 v[102:105], v[168:171], v[192:195], v[102:105]
	v_mfma_f32_16x16x32_bf16 v[98:101], v[176:179], v[192:195], v[98:101]
	v_mfma_f32_16x16x32_bf16 v[86:89], v[168:171], v[200:203], v[86:89]
	v_mfma_f32_16x16x32_bf16 v[82:85], v[176:179], v[200:203], v[82:85]
	v_mfma_f32_16x16x32_bf16 v[70:73], v[168:171], v[208:211], v[70:73]
	v_mfma_f32_16x16x32_bf16 v[66:69], v[176:179], v[208:211], v[66:69]
	s_setprio 0
	s_barrier
	s_add_i32 s18, s42, s29
	v_lshl_add_u64 v[212:213], s[22:23], 0, v[130:131]
	s_mov_b32 m0, s18
	ds_read_b128 v[180:183], v150 offset:16384
	ds_read_b128 v[184:187], v150 offset:17408
	ds_read_b128 v[188:191], v150 offset:18432
	ds_read_b128 v[192:195], v150 offset:19456
	ds_read_b128 v[196:199], v150 offset:20480
	ds_read_b128 v[200:203], v150 offset:21504
	ds_read_b128 v[204:207], v150 offset:22528
	ds_read_b128 v[208:211], v150 offset:23552
	global_load_lds_dwordx4 v[212:213], off
	s_add_i32 m0, s18, 0x2000
	s_add_u32 s18, s22, 0x160000
	v_lshl_add_u64 v[214:215], s[22:23], 0, v[132:133]
	s_addc_u32 s19, s23, 0
	s_add_i32 s50, s43, s29
	global_load_lds_dwordx4 v[214:215], off
	v_lshl_add_u64 v[216:217], s[18:19], 0, v[130:131]
	s_mov_b32 m0, s50
	v_lshl_add_u64 v[218:219], s[24:25], 0, v[132:133]
	global_load_lds_dwordx4 v[216:217], off
	v_lshl_add_u64 v[216:217], s[18:19], 0, v[132:133]
	s_add_i32 m0, s50, 0x2000
	s_nop 0
	global_load_lds_dwordx4 v[216:217], off
	v_lshl_add_u64 v[216:217], s[24:25], 0, v[130:131]
	s_mov_b32 m0, s30
	s_nop 0
	global_load_lds_dwordx4 v[216:217], off
	s_mov_b32 m0, s31
	s_nop 0
	global_load_lds_dwordx4 v[218:219], off
	s_waitcnt vmcnt(8)
	s_waitcnt lgkmcnt(0)
	s_barrier
	s_setprio 1
	s_waitcnt lgkmcnt(0)
	v_mfma_f32_16x16x32_bf16 v[62:65], v[142:145], v[180:183], v[62:65]
	v_mfma_f32_16x16x32_bf16 v[58:61], v[156:159], v[180:183], v[58:61]
	v_mfma_f32_16x16x32_bf16 v[46:49], v[142:145], v[188:191], v[46:49]
	v_mfma_f32_16x16x32_bf16 v[42:45], v[156:159], v[188:191], v[42:45]
	v_mfma_f32_16x16x32_bf16 v[30:33], v[142:145], v[196:199], v[30:33]
	v_mfma_f32_16x16x32_bf16 v[26:29], v[156:159], v[196:199], v[26:29]
	v_mfma_f32_16x16x32_bf16 v[14:17], v[142:145], v[204:207], v[14:17]
	v_mfma_f32_16x16x32_bf16 v[10:13], v[156:159], v[204:207], v[10:13]
	v_mfma_f32_16x16x32_bf16 v[62:65], v[152:155], v[184:187], v[62:65]
	v_mfma_f32_16x16x32_bf16 v[58:61], v[160:163], v[184:187], v[58:61]
	v_mfma_f32_16x16x32_bf16 v[46:49], v[152:155], v[192:195], v[46:49]
	v_mfma_f32_16x16x32_bf16 v[42:45], v[160:163], v[192:195], v[42:45]
	v_mfma_f32_16x16x32_bf16 v[30:33], v[152:155], v[200:203], v[30:33]
	v_mfma_f32_16x16x32_bf16 v[26:29], v[160:163], v[200:203], v[26:29]
	v_mfma_f32_16x16x32_bf16 v[14:17], v[152:155], v[208:211], v[14:17]
	v_mfma_f32_16x16x32_bf16 v[10:13], v[160:163], v[208:211], v[10:13]
	s_setprio 0
	s_setprio 1
	v_mfma_f32_16x16x32_bf16 v[54:57], v[164:167], v[180:183], v[54:57]
	v_mfma_f32_16x16x32_bf16 v[50:53], v[172:175], v[180:183], v[50:53]
	v_mfma_f32_16x16x32_bf16 v[38:41], v[164:167], v[188:191], v[38:41]
	v_mfma_f32_16x16x32_bf16 v[34:37], v[172:175], v[188:191], v[34:37]
	v_mfma_f32_16x16x32_bf16 v[22:25], v[164:167], v[196:199], v[22:25]
	v_mfma_f32_16x16x32_bf16 v[18:21], v[172:175], v[196:199], v[18:21]
	v_mfma_f32_16x16x32_bf16 v[6:9], v[164:167], v[204:207], v[6:9]
	v_mfma_f32_16x16x32_bf16 v[2:5], v[172:175], v[204:207], v[2:5]
	v_mfma_f32_16x16x32_bf16 v[54:57], v[168:171], v[184:187], v[54:57]
	v_mfma_f32_16x16x32_bf16 v[50:53], v[176:179], v[184:187], v[50:53]
	v_mfma_f32_16x16x32_bf16 v[38:41], v[168:171], v[192:195], v[38:41]
	v_mfma_f32_16x16x32_bf16 v[34:37], v[176:179], v[192:195], v[34:37]
	v_mfma_f32_16x16x32_bf16 v[22:25], v[168:171], v[200:203], v[22:25]
	v_mfma_f32_16x16x32_bf16 v[18:21], v[176:179], v[200:203], v[18:21]
	v_mfma_f32_16x16x32_bf16 v[6:9], v[168:171], v[208:211], v[6:9]
	v_mfma_f32_16x16x32_bf16 v[2:5], v[176:179], v[208:211], v[2:5]
	s_setprio 0
	s_barrier
	s_add_i32 s50, 0, 0x18000
	s_add_i32 s51, 0, 0x1c000
	v_add_u32_e32 v160, s50, v147
	v_add_u32_e32 v176, s51, v147
	ds_read_b128 v[142:145], v160
	ds_read_b128 v[152:155], v160 offset:1024
	ds_read_b128 v[156:159], v160 offset:2048
	ds_read_b128 v[160:163], v160 offset:3072
	ds_read_b128 v[164:167], v176
	ds_read_b128 v[168:171], v176 offset:1024
	ds_read_b128 v[172:175], v176 offset:2048
	ds_read_b128 v[176:179], v176 offset:3072
	s_add_u32 s18, s24, 0x160000
	s_addc_u32 s19, s25, 0
	s_mov_b32 m0, s33
	v_lshl_add_u64 v[220:221], s[18:19], 0, v[130:131]
	ds_read_b128 v[180:183], v150 offset:32768
	ds_read_b128 v[184:187], v150 offset:33792
	ds_read_b128 v[188:191], v150 offset:34816
	ds_read_b128 v[192:195], v150 offset:35840
	ds_read_b128 v[196:199], v150 offset:36864
	ds_read_b128 v[200:203], v150 offset:37888
	ds_read_b128 v[204:207], v150 offset:38912
	ds_read_b128 v[208:211], v150 offset:39936
	global_load_lds_dwordx4 v[220:221], off
	v_lshl_add_u64 v[220:221], s[18:19], 0, v[132:133]
	s_mov_b32 m0, s34
	s_nop 0
	global_load_lds_dwordx4 v[220:221], off
	s_waitcnt vmcnt(8)
	s_waitcnt lgkmcnt(0)
	s_barrier
	s_setprio 1
	s_waitcnt lgkmcnt(0)
	v_mfma_f32_16x16x32_bf16 v[126:129], v[142:145], v[180:183], v[126:129]
	v_mfma_f32_16x16x32_bf16 v[122:125], v[156:159], v[180:183], v[122:125]
	v_mfma_f32_16x16x32_bf16 v[110:113], v[142:145], v[188:191], v[110:113]
	v_mfma_f32_16x16x32_bf16 v[106:109], v[156:159], v[188:191], v[106:109]
	v_mfma_f32_16x16x32_bf16 v[94:97], v[142:145], v[196:199], v[94:97]
	v_mfma_f32_16x16x32_bf16 v[90:93], v[156:159], v[196:199], v[90:93]
	v_mfma_f32_16x16x32_bf16 v[78:81], v[142:145], v[204:207], v[78:81]
	v_mfma_f32_16x16x32_bf16 v[74:77], v[156:159], v[204:207], v[74:77]
	v_mfma_f32_16x16x32_bf16 v[126:129], v[152:155], v[184:187], v[126:129]
	v_mfma_f32_16x16x32_bf16 v[122:125], v[160:163], v[184:187], v[122:125]
	v_mfma_f32_16x16x32_bf16 v[110:113], v[152:155], v[192:195], v[110:113]
	v_mfma_f32_16x16x32_bf16 v[106:109], v[160:163], v[192:195], v[106:109]
	v_mfma_f32_16x16x32_bf16 v[94:97], v[152:155], v[200:203], v[94:97]
	v_mfma_f32_16x16x32_bf16 v[90:93], v[160:163], v[200:203], v[90:93]
	v_mfma_f32_16x16x32_bf16 v[78:81], v[152:155], v[208:211], v[78:81]
	v_mfma_f32_16x16x32_bf16 v[74:77], v[160:163], v[208:211], v[74:77]
	s_setprio 0
	s_setprio 1
	v_mfma_f32_16x16x32_bf16 v[118:121], v[164:167], v[180:183], v[118:121]
	v_mfma_f32_16x16x32_bf16 v[114:117], v[172:175], v[180:183], v[114:117]
	v_mfma_f32_16x16x32_bf16 v[102:105], v[164:167], v[188:191], v[102:105]
	v_mfma_f32_16x16x32_bf16 v[98:101], v[172:175], v[188:191], v[98:101]
	v_mfma_f32_16x16x32_bf16 v[86:89], v[164:167], v[196:199], v[86:89]
	v_mfma_f32_16x16x32_bf16 v[82:85], v[172:175], v[196:199], v[82:85]
	v_mfma_f32_16x16x32_bf16 v[70:73], v[164:167], v[204:207], v[70:73]
	v_mfma_f32_16x16x32_bf16 v[66:69], v[172:175], v[204:207], v[66:69]
	v_mfma_f32_16x16x32_bf16 v[118:121], v[168:171], v[184:187], v[118:121]
	v_mfma_f32_16x16x32_bf16 v[114:117], v[176:179], v[184:187], v[114:117]
	v_mfma_f32_16x16x32_bf16 v[102:105], v[168:171], v[192:195], v[102:105]
	v_mfma_f32_16x16x32_bf16 v[98:101], v[176:179], v[192:195], v[98:101]
	v_mfma_f32_16x16x32_bf16 v[86:89], v[168:171], v[200:203], v[86:89]
	v_mfma_f32_16x16x32_bf16 v[82:85], v[176:179], v[200:203], v[82:85]
	v_mfma_f32_16x16x32_bf16 v[70:73], v[168:171], v[208:211], v[70:73]
	v_mfma_f32_16x16x32_bf16 v[66:69], v[176:179], v[208:211], v[66:69]
	s_setprio 0
	s_barrier
	s_add_i32 s18, s50, s29
	v_lshl_add_u64 v[212:213], v[212:213], 0, s[12:13]
	s_mov_b32 m0, s18
	ds_read_b128 v[180:183], v150 offset:49152
	ds_read_b128 v[184:187], v150 offset:50176
	ds_read_b128 v[188:191], v150 offset:51200
	ds_read_b128 v[192:195], v150 offset:52224
	ds_read_b128 v[196:199], v150 offset:53248
	ds_read_b128 v[200:203], v150 offset:54272
	ds_read_b128 v[204:207], v150 offset:55296
	ds_read_b128 v[208:211], v150 offset:56320
	global_load_lds_dwordx4 v[212:213], off
	s_add_i32 m0, s18, 0x2000
	s_add_u32 s18, s22, 0x160080
	v_lshl_add_u64 v[212:213], v[214:215], 0, s[12:13]
	s_addc_u32 s19, s23, 0
	s_add_i32 s22, s51, s29
	global_load_lds_dwordx4 v[212:213], off
	v_lshl_add_u64 v[212:213], s[18:19], 0, v[130:131]
	s_mov_b32 m0, s22
	s_nop 0
	global_load_lds_dwordx4 v[212:213], off
	v_lshl_add_u64 v[212:213], s[18:19], 0, v[132:133]
	s_add_i32 m0, s22, 0x2000
	s_nop 0
	global_load_lds_dwordx4 v[212:213], off
	v_lshl_add_u64 v[212:213], v[216:217], 0, s[12:13]
	s_mov_b32 m0, s38
	s_nop 0
	global_load_lds_dwordx4 v[212:213], off
	v_lshl_add_u64 v[212:213], v[218:219], 0, s[12:13]
	s_mov_b32 m0, s39
	s_nop 0
	global_load_lds_dwordx4 v[212:213], off
	s_waitcnt vmcnt(8)
	s_waitcnt lgkmcnt(0)
	s_barrier
	s_setprio 1
	s_waitcnt lgkmcnt(0)
	v_mfma_f32_16x16x32_bf16 v[62:65], v[142:145], v[180:183], v[62:65]
	v_mfma_f32_16x16x32_bf16 v[58:61], v[156:159], v[180:183], v[58:61]
	v_mfma_f32_16x16x32_bf16 v[46:49], v[142:145], v[188:191], v[46:49]
	v_mfma_f32_16x16x32_bf16 v[42:45], v[156:159], v[188:191], v[42:45]
	v_mfma_f32_16x16x32_bf16 v[30:33], v[142:145], v[196:199], v[30:33]
	v_mfma_f32_16x16x32_bf16 v[26:29], v[156:159], v[196:199], v[26:29]
	v_mfma_f32_16x16x32_bf16 v[14:17], v[142:145], v[204:207], v[14:17]
	v_mfma_f32_16x16x32_bf16 v[10:13], v[156:159], v[204:207], v[10:13]
	v_mfma_f32_16x16x32_bf16 v[62:65], v[152:155], v[184:187], v[62:65]
	v_mfma_f32_16x16x32_bf16 v[58:61], v[160:163], v[184:187], v[58:61]
	v_mfma_f32_16x16x32_bf16 v[46:49], v[152:155], v[192:195], v[46:49]
	v_mfma_f32_16x16x32_bf16 v[42:45], v[160:163], v[192:195], v[42:45]
	v_mfma_f32_16x16x32_bf16 v[30:33], v[152:155], v[200:203], v[30:33]
	v_mfma_f32_16x16x32_bf16 v[26:29], v[160:163], v[200:203], v[26:29]
	v_mfma_f32_16x16x32_bf16 v[14:17], v[152:155], v[208:211], v[14:17]
	v_mfma_f32_16x16x32_bf16 v[10:13], v[160:163], v[208:211], v[10:13]
	s_setprio 0
	s_setprio 1
	v_mfma_f32_16x16x32_bf16 v[54:57], v[164:167], v[180:183], v[54:57]
	v_mfma_f32_16x16x32_bf16 v[50:53], v[172:175], v[180:183], v[50:53]
	v_mfma_f32_16x16x32_bf16 v[38:41], v[164:167], v[188:191], v[38:41]
	v_mfma_f32_16x16x32_bf16 v[34:37], v[172:175], v[188:191], v[34:37]
	v_mfma_f32_16x16x32_bf16 v[22:25], v[164:167], v[196:199], v[22:25]
	v_mfma_f32_16x16x32_bf16 v[18:21], v[172:175], v[196:199], v[18:21]
	v_mfma_f32_16x16x32_bf16 v[6:9], v[164:167], v[204:207], v[6:9]
	v_mfma_f32_16x16x32_bf16 v[2:5], v[172:175], v[204:207], v[2:5]
	v_mfma_f32_16x16x32_bf16 v[54:57], v[168:171], v[184:187], v[54:57]
	v_mfma_f32_16x16x32_bf16 v[50:53], v[176:179], v[184:187], v[50:53]
	v_mfma_f32_16x16x32_bf16 v[38:41], v[168:171], v[192:195], v[38:41]
	v_mfma_f32_16x16x32_bf16 v[34:37], v[176:179], v[192:195], v[34:37]
	v_mfma_f32_16x16x32_bf16 v[22:25], v[168:171], v[200:203], v[22:25]
	v_mfma_f32_16x16x32_bf16 v[18:21], v[176:179], v[200:203], v[18:21]
	v_mfma_f32_16x16x32_bf16 v[6:9], v[168:171], v[208:211], v[6:9]
	v_mfma_f32_16x16x32_bf16 v[2:5], v[176:179], v[208:211], v[2:5]
	s_setprio 0
	s_barrier
	s_add_i32 s49, s49, 2
	s_add_u32 s47, s47, 0x100
	s_addc_u32 s48, s48, 0
	s_cmpk_gt_u32 s49, 0x55
	s_mov_b64 s[18:19], s[20:21]
	s_cbranch_scc0 .LBB0_2118
	s_nop 0
	s_and_b64 vcc, exec, s[14:15]
	s_cbranch_vccz .LBB0_2121
	s_barrier
